# v60 + attention tile barrier moved to the end of the row-sum section (hides ds_write latency)
# speedup vs baseline: 1.0110x; 1.0043x over previous
.LBB0_368:
	s_add_i32 s11, s11, 1
	v_lshl_add_u64 v[218:219], v[218:219], 0, s[84:85]
	v_lshl_add_u64 v[220:221], v[220:221], 0, 64
	v_pk_add_f32 v[110:111], v[228:229], 0 op_sel_hi:[1,0]
	v_pk_add_f32 v[232:233], v[144:145], 0 op_sel_hi:[1,0]
	v_pk_add_f32 v[110:111], v[154:155], v[110:111]
	v_pk_add_f32 v[232:233], v[142:143], v[232:233]
	v_pk_add_f32 v[110:111], v[226:227], v[110:111]
	v_pk_add_f32 v[232:233], v[146:147], v[232:233]
	v_pk_add_f32 v[110:111], v[118:119], v[110:111]
	v_pk_add_f32 v[232:233], v[114:115], v[232:233]
	v_pk_add_f32 v[110:111], v[224:225], v[110:111]
	v_pk_add_f32 v[232:233], v[148:149], v[232:233]
	v_pk_add_f32 v[96:97], v[96:97], v[110:111]
	v_pk_add_f32 v[232:233], v[112:113], v[232:233]
	v_pk_add_f32 v[96:97], v[230:231], v[96:97]
	v_pk_add_f32 v[232:233], v[150:151], v[232:233]
	v_pk_add_f32 v[96:97], v[156:157], v[96:97]
	v_pk_add_f32 v[232:233], v[116:117], v[232:233]
	v_pk_add_f32 v[96:97], v[152:153], v[96:97]
	v_pk_add_f32 v[232:233], v[132:133], v[232:233]
	v_pk_add_f32 v[96:97], v[122:123], v[96:97]
	v_pk_add_f32 v[102:103], v[102:103], v[232:233]
	v_pk_add_f32 v[96:97], v[138:139], v[96:97]
	v_pk_add_f32 v[102:103], v[130:131], v[102:103]
	v_pk_add_f32 v[96:97], v[106:107], v[96:97]
	v_pk_add_f32 v[100:101], v[100:101], v[102:103]
	v_pk_add_f32 v[96:97], v[136:137], v[96:97]
	v_pk_add_f32 v[100:101], v[128:129], v[100:101]
	v_pk_add_f32 v[96:97], v[104:105], v[96:97]
	v_pk_add_f32 v[98:99], v[98:99], v[100:101]
	v_pk_add_f32 v[96:97], v[140:141], v[96:97]
	v_pk_add_f32 v[98:99], v[134:135], v[98:99]
	v_pk_add_f32 v[96:97], v[108:109], v[96:97]
	v_pk_add_f32 v[98:99], v[120:121], v[98:99]
	v_pk_add_f32 v[96:97], v[96:97], v[96:97] op_sel:[0,1] op_sel_hi:[1,0]
	v_pk_add_f32 v[98:99], v[98:99], v[98:99] op_sel:[0,1] op_sel_hi:[1,0]
	v_pk_add_f32 v[96:97], v[222:223], v[96:97] op_sel:[1,0] op_sel_hi:[0,1]
	v_pk_add_f32 v[98:99], v[216:217], v[98:99] op_sel:[1,0] op_sel_hi:[0,1]
	s_waitcnt lgkmcnt(0)
	s_barrier
	s_cmp_lg_u32 s11, 36
	s_cbranch_scc0 .LBB0_370
	v_mov_b32_e32 v223, v96
	v_mov_b32_e32 v217, v98
	s_cmp_lt_u32 s11, 35
	s_cselect_b64 s[2:3], -1, 0
	s_cmp_gt_u32 s11, 34
	s_cbranch_scc0 .LBB0_361
	s_branch .LBB0_362
